# GU epilogue row-stat loads issued before the align barrier; MoBA diag-only mask setup skipped on non-diagonal tiles
# speedup vs baseline: 1.0057x; 1.0019x over previous
.LBB0_903:
	s_andn2_b64 vcc, exec, s[38:39]
	s_cbranch_vccnz .LBB0_905
	v_or_b32_e32 v217, s40, v191
	v_or_b32_e32 v220, 2, v217
	v_or_b32_e32 v219, 3, v217
	v_or_b32_e32 v218, 16, v217
	v_or_b32_e32 v216, 17, v217
	v_or_b32_e32 v215, 18, v217
	v_or_b32_e32 v214, 19, v217
	v_or_b32_e32 v213, 32, v217
	v_or_b32_e32 v212, 33, v217
	v_or_b32_e32 v211, 34, v217
	v_or_b32_e32 v210, 35, v217
	v_cmp_gt_i32_e64 s[40:41], v217, v149
	v_cmp_lt_i32_e64 s[38:39], v217, v149
	v_cmp_le_i32_e64 s[58:59], v220, v149
	v_cmp_le_i32_e64 s[60:61], v219, v149
	v_cmp_gt_i32_e64 s[50:51], v218, v149
	v_cmp_le_i32_e64 s[52:53], v216, v149
	v_cmp_le_i32_e64 s[54:55], v215, v149
	v_cmp_le_i32_e64 s[56:57], v214, v149
	v_cmp_gt_i32_e64 s[42:43], v213, v149
	v_cmp_le_i32_e64 s[44:45], v212, v149
	v_cmp_le_i32_e64 s[46:47], v211, v149
	v_cmp_le_i32_e64 s[48:49], v210, v149
	v_mov_b32_e32 v194, s3
	v_cndmask_b32_e64 v154, v132, v194, s[40:41]
	v_cndmask_b32_e64 v204, v188, v133, s[38:39]
	v_or_b32_e32 v133, 48, v217
	v_cndmask_b32_e64 v208, v154, v132, s[38:39]
	v_mov_b32_e32 v132, s3
	v_cmp_gt_i32_e32 vcc, v133, v149
	v_cndmask_b32_e64 v207, v136, v132, s[50:51]
	v_cndmask_b32_e64 v206, v140, v132, s[42:43]
	v_cndmask_b32_e32 v209, v144, v132, vcc
	v_or_b32_e32 v132, 49, v217
	v_cmp_le_i32_e32 vcc, v132, v149
	v_or_b32_e32 v132, 50, v217
	v_cndmask_b32_e64 v200, v188, v134, s[58:59]
	v_cndmask_b32_e32 v205, v188, v145, vcc
	v_cmp_le_i32_e32 vcc, v132, v149
	v_or_b32_e32 v132, 51, v217
	v_cndmask_b32_e64 v195, v188, v135, s[60:61]
	v_cndmask_b32_e32 v201, v188, v146, vcc
	v_cmp_le_i32_e32 vcc, v132, v149
	v_cndmask_b32_e64 v203, v188, v137, s[52:53]
	v_cndmask_b32_e64 v199, v188, v138, s[54:55]
	v_cndmask_b32_e64 v196, v188, v139, s[56:57]
	v_cndmask_b32_e64 v202, v188, v141, s[44:45]
	v_cndmask_b32_e64 v197, v188, v142, s[46:47]
	v_cndmask_b32_e64 v194, v188, v143, s[48:49]
	v_cndmask_b32_e32 v198, v188, v147, vcc

.LBB0_943:
	s_add_u32 s4, s36, 0xfff80080
	s_addc_u32 s5, s37, -1
	s_add_i32 s53, 0, 0x10000
	s_cmp_eq_u32 s52, 28
	s_cselect_b32 s41, s17, s5
	s_cselect_b32 s40, s27, s4
	v_add_u32_e32 v8, s53, v178
	s_cselect_b32 s5, s25, s51
	s_cselect_b32 s4, s49, s50
	s_add_i32 s56, 0, 0x14000
	ds_read_b128 v[142:145], v8
	ds_read_b128 v[146:149], v8 offset:1024
	ds_read_b128 v[150:153], v8 offset:2048
	ds_read_b128 v[172:175], v8 offset:3072
	v_add_u32_e32 v8, s56, v178
	ds_read_b128 v[190:193], v8
	ds_read_b128 v[194:197], v8 offset:1024
	ds_read_b128 v[198:201], v8 offset:2048
	ds_read_b128 v[202:205], v8 offset:3072
	v_lshl_add_u64 v[176:177], s[36:37], 0, v[140:141]
	s_add_i32 m0, s35, 0xc000
	ds_read_b128 v[206:209], v180
	ds_read_b128 v[210:213], v180 offset:1024
	ds_read_b128 v[214:217], v180 offset:2048
	ds_read_b128 v[218:221], v180 offset:3072
	ds_read_b128 v[226:229], v180 offset:4096
	ds_read_b128 v[230:233], v180 offset:5120
	ds_read_b128 v[234:237], v180 offset:6144
	ds_read_b128 v[238:241], v180 offset:7168
	global_load_lds_dwordx4 v[176:177], off
	v_lshl_add_u64 v[176:177], s[36:37], 0, v[138:139]
	s_add_i32 m0, s35, 0xe000
	s_nop 0
	global_load_lds_dwordx4 v[176:177], off
	s_waitcnt vmcnt(8)
	s_waitcnt lgkmcnt(0)
	s_barrier
	s_setprio 1
	s_waitcnt lgkmcnt(0)
	v_mfma_f32_16x16x32_bf16 v[126:129], v[142:145], v[206:209], v[126:129]
	v_mfma_f32_16x16x32_bf16 v[118:121], v[150:153], v[206:209], v[118:121]
	v_mfma_f32_16x16x32_bf16 v[106:109], v[142:145], v[214:217], v[106:109]
	v_mfma_f32_16x16x32_bf16 v[98:101], v[150:153], v[214:217], v[98:101]
	v_mfma_f32_16x16x32_bf16 v[90:93], v[142:145], v[226:229], v[90:93]
	v_mfma_f32_16x16x32_bf16 v[82:85], v[150:153], v[226:229], v[82:85]
	v_mfma_f32_16x16x32_bf16 v[74:77], v[142:145], v[234:237], v[74:77]
	v_mfma_f32_16x16x32_bf16 v[66:69], v[150:153], v[234:237], v[66:69]
	v_mfma_f32_16x16x32_bf16 v[126:129], v[146:149], v[210:213], v[126:129]
	v_mfma_f32_16x16x32_bf16 v[118:121], v[172:175], v[210:213], v[118:121]
	v_mfma_f32_16x16x32_bf16 v[106:109], v[146:149], v[218:221], v[106:109]
	v_mfma_f32_16x16x32_bf16 v[98:101], v[172:175], v[218:221], v[98:101]
	v_mfma_f32_16x16x32_bf16 v[90:93], v[146:149], v[230:233], v[90:93]
	v_mfma_f32_16x16x32_bf16 v[82:85], v[172:175], v[230:233], v[82:85]
	v_mfma_f32_16x16x32_bf16 v[74:77], v[146:149], v[238:241], v[74:77]
	v_mfma_f32_16x16x32_bf16 v[66:69], v[172:175], v[238:241], v[66:69]
	s_setprio 0
	s_setprio 1
	v_mfma_f32_16x16x32_bf16 v[122:125], v[190:193], v[206:209], v[122:125]
	v_mfma_f32_16x16x32_bf16 v[114:117], v[198:201], v[206:209], v[114:117]
	v_mfma_f32_16x16x32_bf16 v[110:113], v[190:193], v[214:217], v[110:113]
	v_mfma_f32_16x16x32_bf16 v[102:105], v[198:201], v[214:217], v[102:105]
	v_mfma_f32_16x16x32_bf16 v[94:97], v[190:193], v[226:229], v[94:97]
	v_mfma_f32_16x16x32_bf16 v[86:89], v[198:201], v[226:229], v[86:89]
	v_mfma_f32_16x16x32_bf16 v[78:81], v[190:193], v[234:237], v[78:81]
	v_mfma_f32_16x16x32_bf16 v[70:73], v[198:201], v[234:237], v[70:73]
	v_mfma_f32_16x16x32_bf16 v[122:125], v[194:197], v[210:213], v[122:125]
	v_mfma_f32_16x16x32_bf16 v[114:117], v[202:205], v[210:213], v[114:117]
	v_mfma_f32_16x16x32_bf16 v[110:113], v[194:197], v[218:221], v[110:113]
	v_mfma_f32_16x16x32_bf16 v[102:105], v[202:205], v[218:221], v[102:105]
	v_mfma_f32_16x16x32_bf16 v[94:97], v[194:197], v[230:233], v[94:97]
	v_mfma_f32_16x16x32_bf16 v[86:89], v[202:205], v[230:233], v[86:89]
	v_mfma_f32_16x16x32_bf16 v[78:81], v[194:197], v[238:241], v[78:81]
	v_mfma_f32_16x16x32_bf16 v[70:73], v[202:205], v[238:241], v[70:73]
	s_setprio 0
	s_barrier
	s_add_i32 s53, s53, s8
	v_lshl_add_u64 v[176:177], s[4:5], 0, v[134:135]
	s_mov_b32 m0, s53
	ds_read_b128 v[206:209], v180 offset:16384
	ds_read_b128 v[210:213], v180 offset:17408
	ds_read_b128 v[214:217], v180 offset:18432
	ds_read_b128 v[218:221], v180 offset:19456
	ds_read_b128 v[226:229], v180 offset:20480
	ds_read_b128 v[230:233], v180 offset:21504
	ds_read_b128 v[234:237], v180 offset:22528
	ds_read_b128 v[238:241], v180 offset:23552
	global_load_lds_dwordx4 v[176:177], off
	s_add_i32 m0, s53, 0x2000
	s_add_u32 s54, s4, 0x80000
	v_lshl_add_u64 v[222:223], s[4:5], 0, v[130:131]
	s_addc_u32 s55, s5, 0
	s_add_i32 s53, s56, s8
	global_load_lds_dwordx4 v[222:223], off
	v_lshl_add_u64 v[242:243], s[54:55], 0, v[134:135]
	s_mov_b32 m0, s53
	v_lshl_add_u64 v[244:245], s[40:41], 0, v[132:133]
	global_load_lds_dwordx4 v[242:243], off
	v_lshl_add_u64 v[242:243], s[54:55], 0, v[130:131]
	s_add_i32 m0, s53, 0x2000
	s_nop 0
	global_load_lds_dwordx4 v[242:243], off
	v_lshl_add_u64 v[242:243], s[40:41], 0, v[136:137]
	s_mov_b32 m0, s35
	s_nop 0
	global_load_lds_dwordx4 v[242:243], off
	s_mov_b32 m0, s42
	s_nop 0
	global_load_lds_dwordx4 v[244:245], off
	s_waitcnt vmcnt(8)
	s_waitcnt lgkmcnt(0)
	s_barrier
	s_setprio 1
	s_waitcnt lgkmcnt(0)
	v_mfma_f32_16x16x32_bf16 v[58:61], v[142:145], v[206:209], v[58:61]
	v_mfma_f32_16x16x32_bf16 v[50:53], v[150:153], v[206:209], v[50:53]
	v_mfma_f32_16x16x32_bf16 v[42:45], v[142:145], v[214:217], v[42:45]
	v_mfma_f32_16x16x32_bf16 v[34:37], v[150:153], v[214:217], v[34:37]
	v_mfma_f32_16x16x32_bf16 v[26:29], v[142:145], v[226:229], v[26:29]
	v_mfma_f32_16x16x32_bf16 v[18:21], v[150:153], v[226:229], v[18:21]
	v_mfma_f32_16x16x32_bf16 v[10:13], v[142:145], v[234:237], v[10:13]
	v_mfma_f32_16x16x32_bf16 v[4:7], v[150:153], v[234:237], v[4:7]
	v_mfma_f32_16x16x32_bf16 v[58:61], v[146:149], v[210:213], v[58:61]
	v_mfma_f32_16x16x32_bf16 v[50:53], v[172:175], v[210:213], v[50:53]
	v_mfma_f32_16x16x32_bf16 v[42:45], v[146:149], v[218:221], v[42:45]
	v_mfma_f32_16x16x32_bf16 v[34:37], v[172:175], v[218:221], v[34:37]
	v_mfma_f32_16x16x32_bf16 v[26:29], v[146:149], v[230:233], v[26:29]
	v_mfma_f32_16x16x32_bf16 v[18:21], v[172:175], v[230:233], v[18:21]
	v_mfma_f32_16x16x32_bf16 v[10:13], v[146:149], v[238:241], v[10:13]
	v_mfma_f32_16x16x32_bf16 v[4:7], v[172:175], v[238:241], v[4:7]
	s_setprio 0
	s_setprio 1
	v_mfma_f32_16x16x32_bf16 v[62:65], v[190:193], v[206:209], v[62:65]
	v_mfma_f32_16x16x32_bf16 v[54:57], v[198:201], v[206:209], v[54:57]
	v_mfma_f32_16x16x32_bf16 v[46:49], v[190:193], v[214:217], v[46:49]
	v_mfma_f32_16x16x32_bf16 v[38:41], v[198:201], v[214:217], v[38:41]
	v_mfma_f32_16x16x32_bf16 v[30:33], v[190:193], v[226:229], v[30:33]
	v_mfma_f32_16x16x32_bf16 v[22:25], v[198:201], v[226:229], v[22:25]
	v_mfma_f32_16x16x32_bf16 v[14:17], v[190:193], v[234:237], v[14:17]
	v_mfma_f32_16x16x32_bf16 v[0:3], v[198:201], v[234:237], v[0:3]
	v_mfma_f32_16x16x32_bf16 v[62:65], v[194:197], v[210:213], v[62:65]
	v_mfma_f32_16x16x32_bf16 v[54:57], v[202:205], v[210:213], v[54:57]
	v_mfma_f32_16x16x32_bf16 v[46:49], v[194:197], v[218:221], v[46:49]
	v_mfma_f32_16x16x32_bf16 v[38:41], v[202:205], v[218:221], v[38:41]
	v_mfma_f32_16x16x32_bf16 v[30:33], v[194:197], v[230:233], v[30:33]
	v_mfma_f32_16x16x32_bf16 v[22:25], v[202:205], v[230:233], v[22:25]
	v_mfma_f32_16x16x32_bf16 v[14:17], v[194:197], v[238:241], v[14:17]
	v_mfma_f32_16x16x32_bf16 v[0:3], v[202:205], v[238:241], v[0:3]
	s_setprio 0
	s_barrier
	s_add_i32 s53, 0, 0x18000
	v_add_u32_e32 v8, s53, v178
	s_add_i32 s54, 0, 0x1c000
	ds_read_b128 v[142:145], v8
	ds_read_b128 v[146:149], v8 offset:1024
	ds_read_b128 v[150:153], v8 offset:2048
	ds_read_b128 v[172:175], v8 offset:3072
	v_add_u32_e32 v8, s54, v178
	ds_read_b128 v[190:193], v8
	ds_read_b128 v[194:197], v8 offset:1024
	ds_read_b128 v[198:201], v8 offset:2048
	ds_read_b128 v[202:205], v8 offset:3072
	s_add_u32 s40, s40, 0x80000
	s_addc_u32 s41, s41, 0
	s_mov_b32 m0, s43
	v_lshl_add_u64 v[246:247], s[40:41], 0, v[136:137]
	ds_read_b128 v[206:209], v180 offset:32768
	ds_read_b128 v[210:213], v180 offset:33792
	ds_read_b128 v[214:217], v180 offset:34816
	ds_read_b128 v[218:221], v180 offset:35840
	ds_read_b128 v[226:229], v180 offset:36864
	ds_read_b128 v[230:233], v180 offset:37888
	ds_read_b128 v[234:237], v180 offset:38912
	ds_read_b128 v[238:241], v180 offset:39936
	global_load_lds_dwordx4 v[246:247], off
	v_lshl_add_u64 v[246:247], s[40:41], 0, v[132:133]
	s_mov_b32 m0, s44
	s_nop 0
	global_load_lds_dwordx4 v[246:247], off
	s_waitcnt vmcnt(8)
	s_waitcnt lgkmcnt(0)
	s_barrier
	s_setprio 1
	s_waitcnt lgkmcnt(0)
	v_mfma_f32_16x16x32_bf16 v[126:129], v[142:145], v[206:209], v[126:129]
	v_mfma_f32_16x16x32_bf16 v[118:121], v[150:153], v[206:209], v[118:121]
	v_mfma_f32_16x16x32_bf16 v[106:109], v[142:145], v[214:217], v[106:109]
	v_mfma_f32_16x16x32_bf16 v[98:101], v[150:153], v[214:217], v[98:101]
	v_mfma_f32_16x16x32_bf16 v[90:93], v[142:145], v[226:229], v[90:93]
	v_mfma_f32_16x16x32_bf16 v[82:85], v[150:153], v[226:229], v[82:85]
	v_mfma_f32_16x16x32_bf16 v[74:77], v[142:145], v[234:237], v[74:77]
	v_mfma_f32_16x16x32_bf16 v[66:69], v[150:153], v[234:237], v[66:69]
	v_mfma_f32_16x16x32_bf16 v[126:129], v[146:149], v[210:213], v[126:129]
	v_mfma_f32_16x16x32_bf16 v[118:121], v[172:175], v[210:213], v[118:121]
	v_mfma_f32_16x16x32_bf16 v[106:109], v[146:149], v[218:221], v[106:109]
	v_mfma_f32_16x16x32_bf16 v[98:101], v[172:175], v[218:221], v[98:101]
	v_mfma_f32_16x16x32_bf16 v[90:93], v[146:149], v[230:233], v[90:93]
	v_mfma_f32_16x16x32_bf16 v[82:85], v[172:175], v[230:233], v[82:85]
	v_mfma_f32_16x16x32_bf16 v[74:77], v[146:149], v[238:241], v[74:77]
	v_mfma_f32_16x16x32_bf16 v[66:69], v[172:175], v[238:241], v[66:69]
	s_setprio 0
	s_setprio 1
	v_mfma_f32_16x16x32_bf16 v[122:125], v[190:193], v[206:209], v[122:125]
	v_mfma_f32_16x16x32_bf16 v[114:117], v[198:201], v[206:209], v[114:117]
	v_mfma_f32_16x16x32_bf16 v[110:113], v[190:193], v[214:217], v[110:113]
	v_mfma_f32_16x16x32_bf16 v[102:105], v[198:201], v[214:217], v[102:105]
	v_mfma_f32_16x16x32_bf16 v[94:97], v[190:193], v[226:229], v[94:97]
	v_mfma_f32_16x16x32_bf16 v[86:89], v[198:201], v[226:229], v[86:89]
	v_mfma_f32_16x16x32_bf16 v[78:81], v[190:193], v[234:237], v[78:81]
	v_mfma_f32_16x16x32_bf16 v[70:73], v[198:201], v[234:237], v[70:73]
	v_mfma_f32_16x16x32_bf16 v[122:125], v[194:197], v[210:213], v[122:125]
	v_mfma_f32_16x16x32_bf16 v[114:117], v[202:205], v[210:213], v[114:117]
	v_mfma_f32_16x16x32_bf16 v[110:113], v[194:197], v[218:221], v[110:113]
	v_mfma_f32_16x16x32_bf16 v[102:105], v[202:205], v[218:221], v[102:105]
	v_mfma_f32_16x16x32_bf16 v[94:97], v[194:197], v[230:233], v[94:97]
	v_mfma_f32_16x16x32_bf16 v[86:89], v[202:205], v[230:233], v[86:89]
	v_mfma_f32_16x16x32_bf16 v[78:81], v[194:197], v[238:241], v[78:81]
	v_mfma_f32_16x16x32_bf16 v[70:73], v[202:205], v[238:241], v[70:73]
	s_setprio 0
	s_barrier
	s_add_i32 s40, s53, s8
	v_lshl_add_u64 v[176:177], v[176:177], 0, s[94:95]
	s_mov_b32 m0, s40
	ds_read_b128 v[206:209], v180 offset:49152
	ds_read_b128 v[210:213], v180 offset:50176
	ds_read_b128 v[214:217], v180 offset:51200
	ds_read_b128 v[218:221], v180 offset:52224
	ds_read_b128 v[226:229], v180 offset:53248
	ds_read_b128 v[230:233], v180 offset:54272
	ds_read_b128 v[234:237], v180 offset:55296
	ds_read_b128 v[238:241], v180 offset:56320
	global_load_lds_dwordx4 v[176:177], off
	s_add_i32 m0, s40, 0x2000
	s_add_u32 s4, s4, 0x80080
	v_lshl_add_u64 v[176:177], v[222:223], 0, s[94:95]
	s_addc_u32 s5, s5, 0
	s_add_i32 s40, s54, s8
	global_load_lds_dwordx4 v[176:177], off
	v_lshl_add_u64 v[176:177], s[4:5], 0, v[134:135]
	s_mov_b32 m0, s40
	s_nop 0
	global_load_lds_dwordx4 v[176:177], off
	v_lshl_add_u64 v[176:177], s[4:5], 0, v[130:131]
	s_add_i32 m0, s40, 0x2000
	s_nop 0
	global_load_lds_dwordx4 v[176:177], off
	v_lshl_add_u64 v[176:177], v[242:243], 0, s[94:95]
	s_mov_b32 m0, s45
	s_nop 0
	global_load_lds_dwordx4 v[176:177], off
	v_lshl_add_u64 v[176:177], v[244:245], 0, s[94:95]
	s_mov_b32 m0, s46
	s_nop 0
	global_load_lds_dwordx4 v[176:177], off
	s_waitcnt vmcnt(8)
	s_waitcnt lgkmcnt(0)
	s_barrier
	s_setprio 1
	s_waitcnt lgkmcnt(0)
	v_mfma_f32_16x16x32_bf16 v[58:61], v[142:145], v[206:209], v[58:61]
	v_mfma_f32_16x16x32_bf16 v[50:53], v[150:153], v[206:209], v[50:53]
	v_mfma_f32_16x16x32_bf16 v[42:45], v[142:145], v[214:217], v[42:45]
	v_mfma_f32_16x16x32_bf16 v[34:37], v[150:153], v[214:217], v[34:37]
	v_mfma_f32_16x16x32_bf16 v[26:29], v[142:145], v[226:229], v[26:29]
	v_mfma_f32_16x16x32_bf16 v[18:21], v[150:153], v[226:229], v[18:21]
	v_mfma_f32_16x16x32_bf16 v[10:13], v[142:145], v[234:237], v[10:13]
	v_mfma_f32_16x16x32_bf16 v[4:7], v[150:153], v[234:237], v[4:7]
	v_mfma_f32_16x16x32_bf16 v[58:61], v[146:149], v[210:213], v[58:61]
	v_mfma_f32_16x16x32_bf16 v[50:53], v[172:175], v[210:213], v[50:53]
	v_mfma_f32_16x16x32_bf16 v[42:45], v[146:149], v[218:221], v[42:45]
	v_mfma_f32_16x16x32_bf16 v[34:37], v[172:175], v[218:221], v[34:37]
	v_mfma_f32_16x16x32_bf16 v[26:29], v[146:149], v[230:233], v[26:29]
	v_mfma_f32_16x16x32_bf16 v[18:21], v[172:175], v[230:233], v[18:21]
	v_mfma_f32_16x16x32_bf16 v[10:13], v[146:149], v[238:241], v[10:13]
	v_mfma_f32_16x16x32_bf16 v[4:7], v[172:175], v[238:241], v[4:7]
	s_setprio 0
	s_setprio 1
	v_mfma_f32_16x16x32_bf16 v[62:65], v[190:193], v[206:209], v[62:65]
	v_mfma_f32_16x16x32_bf16 v[54:57], v[198:201], v[206:209], v[54:57]
	v_mfma_f32_16x16x32_bf16 v[46:49], v[190:193], v[214:217], v[46:49]
	v_mfma_f32_16x16x32_bf16 v[38:41], v[198:201], v[214:217], v[38:41]
	v_mfma_f32_16x16x32_bf16 v[30:33], v[190:193], v[226:229], v[30:33]
	v_mfma_f32_16x16x32_bf16 v[22:25], v[198:201], v[226:229], v[22:25]
	v_mfma_f32_16x16x32_bf16 v[14:17], v[190:193], v[234:237], v[14:17]
	v_mfma_f32_16x16x32_bf16 v[0:3], v[198:201], v[234:237], v[0:3]
	v_mfma_f32_16x16x32_bf16 v[62:65], v[194:197], v[210:213], v[62:65]
	v_mfma_f32_16x16x32_bf16 v[54:57], v[202:205], v[210:213], v[54:57]
	v_mfma_f32_16x16x32_bf16 v[46:49], v[194:197], v[218:221], v[46:49]
	v_mfma_f32_16x16x32_bf16 v[38:41], v[202:205], v[218:221], v[38:41]
	v_mfma_f32_16x16x32_bf16 v[30:33], v[194:197], v[230:233], v[30:33]
	v_mfma_f32_16x16x32_bf16 v[22:25], v[202:205], v[230:233], v[22:25]
	v_mfma_f32_16x16x32_bf16 v[14:17], v[194:197], v[238:241], v[14:17]
	v_mfma_f32_16x16x32_bf16 v[0:3], v[202:205], v[238:241], v[0:3]
	s_setprio 0
	s_barrier
	s_add_i32 s52, s52, 2
	s_add_u32 s50, s50, 0x100
	s_addc_u32 s51, s51, 0
	s_add_u32 s36, s36, 0x100
	s_addc_u32 s37, s37, 0
	s_cmp_gt_u32 s52, 29
	s_cbranch_scc0 .LBB0_943
	v_lshl_add_u32 v142, s34, 8, v171
	v_ashrrev_i32_e32 v143, 31, v142
	v_lshl_add_u64 v[144:145], v[142:143], 3, s[20:21]
	global_load_dwordx2 v[190:191], v[144:145], off
	global_load_dwordx2 v[174:175], v[144:145], off offset:128
	global_load_dwordx2 v[172:173], v[144:145], off offset:256
	global_load_dwordx2 v[152:153], v[144:145], off offset:384
	global_load_dwordx2 v[150:151], v[144:145], off offset:1024
	global_load_dwordx2 v[148:149], v[144:145], off offset:1152
	global_load_dwordx2 v[146:147], v[144:145], off offset:1280
	s_nop 0
	global_load_dwordx2 v[144:145], v[144:145], off offset:1408
	s_and_b64 vcc, exec, s[22:23]
	s_cbranch_vccz .LBB0_946
	s_barrier
.LBB0_946:
	s_min_u32 s4, s85, 32
	s_sub_i32 s5, 32, s4
	v_pk_mul_f32 v[122:123], v[126:127], v[122:123]
	v_pk_mul_f32 v[124:125], v[128:129], v[124:125]
	v_pk_mul_f32 v[114:115], v[118:119], v[114:115]
	v_lshl_or_b32 v176, s16, 7, v179
	v_readlane_b32 s16, v252, 0
	v_pk_mul_f32 v[116:117], v[120:121], v[116:117]
	v_readlane_b32 s17, v252, 1
	v_ashrrev_i32_e32 v177, 31, v176
	v_pk_mul_f32 v[112:113], v[108:109], v[112:113]
	v_pk_mul_f32 v[104:105], v[100:101], v[104:105]
	v_pk_mul_f32 v[96:97], v[92:93], v[96:97]
	v_pk_mul_f32 v[88:89], v[84:85], v[88:89]
	v_pk_mul_f32 v[80:81], v[76:77], v[80:81]
	v_pk_mul_f32 v[72:73], v[68:69], v[72:73]
	v_pk_mul_f32 v[64:65], v[60:61], v[64:65]
	v_add_u32_e32 v143, 0x80, v142
	v_pk_mul_f32 v[56:57], v[52:53], v[56:57]
	v_pk_mul_f32 v[48:49], v[44:45], v[48:49]
	v_pk_mul_f32 v[40:41], v[36:37], v[40:41]
	v_pk_mul_f32 v[32:33], v[28:29], v[32:33]
	v_pk_mul_f32 v[24:25], v[20:21], v[24:25]
	v_pk_mul_f32 v[0:1], v[4:5], v[0:1]
	v_pk_mul_f32 v[16:17], v[12:13], v[16:17]
	v_pk_mul_f32 v[2:3], v[6:7], v[2:3]
	s_andn2_b64 vcc, exec, s[38:39]
	s_waitcnt vmcnt(0)
	v_mov_b32_e32 v8, v191
	v_lshlrev_b64 v[192:193], s4, v[8:9]
	v_min_u32_e32 v8, 1, v192
	v_or_b32_e32 v8, v193, v8
	v_cvt_f32_u32_e32 v8, v8
	v_cvt_f32_u32_e32 v154, v190
	v_ldexp_f32 v8, v8, s5
	v_fmac_f32_e32 v8, 0x2f800000, v154
	v_fmamk_f32 v8, v8, 0x3a000000, v183
	v_rsq_f32_e32 v154, v8
	s_nop 0
	v_mul_f32_e32 v8, v154, v154
	v_mul_f32_e32 v154, 0xbfb8aa3b, v154
	v_mul_f32_e32 v155, v126, v154
	v_exp_f32_e32 v155, v155
	s_nop 0
	v_add_f32_e32 v155, 1.0, v155
	v_rcp_f32_e32 v190, v155
	v_mul_f32_e32 v155, v127, v154
	v_exp_f32_e32 v155, v155
	s_nop 0
	v_add_f32_e32 v155, 1.0, v155
	v_rcp_f32_e32 v191, v155
	s_nop 0
	v_pk_mul_f32 v[126:127], v[8:9], v[190:191] op_sel_hi:[0,1]
	v_pk_mul_f32 v[122:123], v[122:123], v[126:127]
	v_mul_f32_e32 v126, v128, v154
	v_mul_f32_e32 v127, v129, v154
	v_exp_f32_e32 v126, v126
	v_exp_f32_e32 v127, v127
	v_add_f32_e32 v126, 1.0, v126
	v_add_f32_e32 v127, 1.0, v127
	v_rcp_f32_e32 v126, v126
	v_rcp_f32_e32 v127, v127
	s_nop 0
	v_pk_mul_f32 v[126:127], v[8:9], v[126:127] op_sel_hi:[0,1]
	v_pk_mul_f32 v[124:125], v[124:125], v[126:127]
	v_mul_f32_e32 v126, v118, v154
	v_mul_f32_e32 v127, v119, v154
	v_exp_f32_e32 v126, v126
	v_exp_f32_e32 v127, v127
	v_add_f32_e32 v126, 1.0, v126
	v_add_f32_e32 v127, 1.0, v127
	v_rcp_f32_e32 v126, v126
	v_rcp_f32_e32 v127, v127
	s_nop 0
	v_pk_mul_f32 v[118:119], v[8:9], v[126:127] op_sel_hi:[0,1]
	v_pk_mul_f32 v[114:115], v[114:115], v[118:119]
	v_mul_f32_e32 v118, v120, v154
	v_mul_f32_e32 v119, v121, v154
	v_exp_f32_e32 v118, v118
	v_exp_f32_e32 v119, v119
	v_cvt_pk_bf16_f32 v120, v114, v115
	v_mov_b64_e32 v[114:115], s[16:17]
	v_add_f32_e32 v118, 1.0, v118
	v_add_f32_e32 v119, 1.0, v119
	v_rcp_f32_e32 v118, v118
	v_rcp_f32_e32 v119, v119
	s_nop 0
	v_pk_mul_f32 v[118:119], v[8:9], v[118:119] op_sel_hi:[0,1]
	v_pk_mul_f32 v[116:117], v[116:117], v[118:119]
	v_cvt_pk_bf16_f32 v118, v122, v123
	v_cvt_pk_bf16_f32 v121, v116, v117
	v_mad_i64_i32 v[122:123], s[16:17], v142, s66, v[114:115]
	v_lshlrev_b64 v[116:117], 1, v[176:177]
	v_cvt_pk_bf16_f32 v119, v124, v125
	v_lshl_add_u64 v[122:123], v[122:123], 0, v[116:117]
	v_mov_b32_e32 v8, v175
	global_store_dwordx4 v[122:123], v[118:121], off
	s_nop 1
	v_lshlrev_b64 v[118:119], s4, v[8:9]
	v_min_u32_e32 v8, 1, v118
	v_or_b32_e32 v8, v119, v8
	v_cvt_f32_u32_e32 v8, v8
	v_cvt_f32_u32_e32 v118, v174
	v_ldexp_f32 v8, v8, s5
	v_fmac_f32_e32 v8, 0x2f800000, v118
	v_fmamk_f32 v8, v8, 0x3a000000, v183
	v_rsq_f32_e32 v118, v8
	s_nop 0
	v_mul_f32_e32 v8, v118, v118
	v_mul_f32_e32 v118, 0xbfb8aa3b, v118
	v_mul_f32_e32 v119, v106, v118
	v_exp_f32_e32 v119, v119
	v_mul_f32_e32 v108, v108, v118
	v_mul_f32_e32 v109, v109, v118
	v_exp_f32_e32 v108, v108
	v_add_f32_e32 v119, 1.0, v119
	v_rcp_f32_e32 v120, v119
	v_mul_f32_e32 v119, v107, v118
	v_exp_f32_e32 v119, v119
	v_pk_mul_f32 v[106:107], v[106:107], v[110:111]
	v_exp_f32_e32 v109, v109
	v_add_f32_e32 v108, 1.0, v108
	v_add_f32_e32 v119, 1.0, v119
	v_rcp_f32_e32 v121, v119
	v_add_f32_e32 v109, 1.0, v109
	v_rcp_f32_e32 v108, v108
	v_rcp_f32_e32 v109, v109
	v_pk_mul_f32 v[110:111], v[8:9], v[120:121] op_sel_hi:[0,1]
	v_pk_mul_f32 v[106:107], v[106:107], v[110:111]
	v_mul_f32_e32 v110, v98, v118
	v_mul_f32_e32 v111, v99, v118
	v_exp_f32_e32 v110, v110
	v_exp_f32_e32 v111, v111
	v_pk_mul_f32 v[98:99], v[98:99], v[102:103]
	v_pk_mul_f32 v[108:109], v[8:9], v[108:109] op_sel_hi:[0,1]
	v_add_f32_e32 v110, 1.0, v110
	v_add_f32_e32 v111, 1.0, v111
	v_rcp_f32_e32 v110, v110
	v_rcp_f32_e32 v111, v111
	v_pk_mul_f32 v[108:109], v[112:113], v[108:109]
	v_pk_mul_f32 v[102:103], v[8:9], v[110:111] op_sel_hi:[0,1]
	v_pk_mul_f32 v[102:103], v[98:99], v[102:103]
	v_mul_f32_e32 v98, v100, v118
	v_mul_f32_e32 v99, v101, v118
	v_exp_f32_e32 v98, v98
	v_exp_f32_e32 v99, v99
	v_cvt_pk_bf16_f32 v100, v102, v103
	v_add_f32_e32 v98, 1.0, v98
	v_add_f32_e32 v99, 1.0, v99
	v_rcp_f32_e32 v98, v98
	v_rcp_f32_e32 v99, v99
	s_nop 0
	v_pk_mul_f32 v[98:99], v[8:9], v[98:99] op_sel_hi:[0,1]
	v_or_b32_e32 v8, 16, v142
	v_pk_mul_f32 v[104:105], v[104:105], v[98:99]
	v_mad_i64_i32 v[102:103], s[16:17], v8, s66, v[114:115]
	v_cvt_pk_bf16_f32 v98, v106, v107
	v_cvt_pk_bf16_f32 v99, v108, v109
	v_cvt_pk_bf16_f32 v101, v104, v105
	v_lshl_add_u64 v[102:103], v[102:103], 0, v[116:117]
	v_mov_b32_e32 v8, v173
	global_store_dwordx4 v[102:103], v[98:101], off
	s_nop 1
	v_lshlrev_b64 v[98:99], s4, v[8:9]
	v_min_u32_e32 v8, 1, v98
	v_or_b32_e32 v8, v99, v8
	v_cvt_f32_u32_e32 v8, v8
	v_cvt_f32_u32_e32 v98, v172
	v_ldexp_f32 v8, v8, s5
	v_fmac_f32_e32 v8, 0x2f800000, v98
	v_fmamk_f32 v8, v8, 0x3a000000, v183
	v_rsq_f32_e32 v98, v8
	s_nop 0
	v_mul_f32_e32 v100, 0xbfb8aa3b, v98
	v_mul_f32_e32 v8, v98, v98
	v_mul_f32_e32 v98, v90, v100
	v_mul_f32_e32 v99, v91, v100
	v_exp_f32_e32 v98, v98
	v_exp_f32_e32 v99, v99
	v_pk_mul_f32 v[90:91], v[90:91], v[94:95]
	v_mul_f32_e32 v92, v92, v100
	v_add_f32_e32 v98, 1.0, v98
	v_add_f32_e32 v99, 1.0, v99
	v_rcp_f32_e32 v98, v98
	v_rcp_f32_e32 v99, v99
	v_mul_f32_e32 v93, v93, v100
	v_exp_f32_e32 v92, v92
	v_exp_f32_e32 v93, v93
	v_pk_mul_f32 v[94:95], v[8:9], v[98:99] op_sel_hi:[0,1]
	v_pk_mul_f32 v[90:91], v[90:91], v[94:95]
	v_mul_f32_e32 v94, v82, v100
	v_mul_f32_e32 v95, v83, v100
	v_exp_f32_e32 v94, v94
	v_exp_f32_e32 v95, v95
	v_pk_mul_f32 v[82:83], v[82:83], v[86:87]
	v_add_f32_e32 v92, 1.0, v92
	v_add_f32_e32 v94, 1.0, v94
	v_add_f32_e32 v95, 1.0, v95
	v_rcp_f32_e32 v94, v94
	v_rcp_f32_e32 v95, v95
	v_add_f32_e32 v93, 1.0, v93
	v_rcp_f32_e32 v92, v92
	v_rcp_f32_e32 v93, v93
	v_pk_mul_f32 v[86:87], v[8:9], v[94:95] op_sel_hi:[0,1]
	v_pk_mul_f32 v[86:87], v[82:83], v[86:87]
	v_mul_f32_e32 v82, v84, v100
	v_mul_f32_e32 v83, v85, v100
	v_exp_f32_e32 v82, v82
	v_exp_f32_e32 v83, v83
	v_pk_mul_f32 v[92:93], v[8:9], v[92:93] op_sel_hi:[0,1]
	v_pk_mul_f32 v[92:93], v[96:97], v[92:93]
	v_add_f32_e32 v82, 1.0, v82
	v_add_f32_e32 v83, 1.0, v83
	v_rcp_f32_e32 v82, v82
	v_rcp_f32_e32 v83, v83
	v_cvt_pk_bf16_f32 v84, v86, v87
	v_pk_mul_f32 v[82:83], v[8:9], v[82:83] op_sel_hi:[0,1]
	v_or_b32_e32 v8, 32, v142
	v_pk_mul_f32 v[88:89], v[88:89], v[82:83]
	v_mad_i64_i32 v[86:87], s[16:17], v8, s66, v[114:115]
	v_cvt_pk_bf16_f32 v82, v90, v91
	v_cvt_pk_bf16_f32 v83, v92, v93
	v_cvt_pk_bf16_f32 v85, v88, v89
	v_lshl_add_u64 v[86:87], v[86:87], 0, v[116:117]
	v_mov_b32_e32 v8, v153
	global_store_dwordx4 v[86:87], v[82:85], off
	s_nop 1
	v_lshlrev_b64 v[82:83], s4, v[8:9]
	v_min_u32_e32 v8, 1, v82
	v_or_b32_e32 v8, v83, v8
	v_cvt_f32_u32_e32 v8, v8
	v_cvt_f32_u32_e32 v82, v152
	v_ldexp_f32 v8, v8, s5
	v_fmac_f32_e32 v8, 0x2f800000, v82
	v_fmamk_f32 v8, v8, 0x3a000000, v183
	v_rsq_f32_e32 v82, v8
	s_nop 0
	v_mul_f32_e32 v84, 0xbfb8aa3b, v82
	v_mul_f32_e32 v8, v82, v82
	v_mul_f32_e32 v82, v74, v84
	v_mul_f32_e32 v83, v75, v84
	v_exp_f32_e32 v82, v82
	v_exp_f32_e32 v83, v83
	v_pk_mul_f32 v[74:75], v[74:75], v[78:79]
	v_mul_f32_e32 v76, v76, v84
	v_add_f32_e32 v82, 1.0, v82
	v_add_f32_e32 v83, 1.0, v83
	v_rcp_f32_e32 v82, v82
	v_rcp_f32_e32 v83, v83
	v_mul_f32_e32 v77, v77, v84
	v_exp_f32_e32 v76, v76
	v_exp_f32_e32 v77, v77
	v_pk_mul_f32 v[78:79], v[8:9], v[82:83] op_sel_hi:[0,1]
	v_pk_mul_f32 v[74:75], v[74:75], v[78:79]
	v_mul_f32_e32 v78, v66, v84
	v_mul_f32_e32 v79, v67, v84
	v_exp_f32_e32 v78, v78
	v_exp_f32_e32 v79, v79
	v_pk_mul_f32 v[66:67], v[66:67], v[70:71]
	v_add_f32_e32 v76, 1.0, v76
	v_add_f32_e32 v78, 1.0, v78
	v_add_f32_e32 v79, 1.0, v79
	v_rcp_f32_e32 v78, v78
	v_rcp_f32_e32 v79, v79
	v_add_f32_e32 v77, 1.0, v77
	v_rcp_f32_e32 v76, v76
	v_rcp_f32_e32 v77, v77
	v_pk_mul_f32 v[70:71], v[8:9], v[78:79] op_sel_hi:[0,1]
	v_pk_mul_f32 v[70:71], v[66:67], v[70:71]
	v_mul_f32_e32 v66, v68, v84
	v_mul_f32_e32 v67, v69, v84
	v_exp_f32_e32 v66, v66
	v_exp_f32_e32 v67, v67
	v_pk_mul_f32 v[76:77], v[8:9], v[76:77] op_sel_hi:[0,1]
	v_pk_mul_f32 v[76:77], v[80:81], v[76:77]
	v_add_f32_e32 v66, 1.0, v66
	v_add_f32_e32 v67, 1.0, v67
	v_rcp_f32_e32 v66, v66
	v_rcp_f32_e32 v67, v67
	v_cvt_pk_bf16_f32 v68, v70, v71
	v_pk_mul_f32 v[66:67], v[8:9], v[66:67] op_sel_hi:[0,1]
	v_or_b32_e32 v8, 48, v142
	v_pk_mul_f32 v[72:73], v[72:73], v[66:67]
	v_mad_i64_i32 v[70:71], s[16:17], v8, s66, v[114:115]
	v_cvt_pk_bf16_f32 v66, v74, v75
	v_cvt_pk_bf16_f32 v67, v76, v77
	v_cvt_pk_bf16_f32 v69, v72, v73
	v_lshl_add_u64 v[70:71], v[70:71], 0, v[116:117]
	v_mov_b32_e32 v8, v151
	global_store_dwordx4 v[70:71], v[66:69], off
	s_nop 1
	v_lshlrev_b64 v[66:67], s4, v[8:9]
	v_min_u32_e32 v8, 1, v66
	v_or_b32_e32 v8, v67, v8
	v_cvt_f32_u32_e32 v8, v8
	v_cvt_f32_u32_e32 v66, v150
	v_ldexp_f32 v8, v8, s5
	v_fmac_f32_e32 v8, 0x2f800000, v66
	v_fmamk_f32 v8, v8, 0x3a000000, v183
	v_rsq_f32_e32 v66, v8
	s_nop 0
	v_mul_f32_e32 v68, 0xbfb8aa3b, v66
	v_mul_f32_e32 v8, v66, v66
	v_mul_f32_e32 v66, v58, v68
	v_mul_f32_e32 v67, v59, v68
	v_exp_f32_e32 v66, v66
	v_exp_f32_e32 v67, v67
	v_pk_mul_f32 v[58:59], v[58:59], v[62:63]
	v_mul_f32_e32 v60, v60, v68
	v_add_f32_e32 v66, 1.0, v66
	v_add_f32_e32 v67, 1.0, v67
	v_rcp_f32_e32 v66, v66
	v_rcp_f32_e32 v67, v67
	v_mul_f32_e32 v61, v61, v68
	v_exp_f32_e32 v60, v60
	v_exp_f32_e32 v61, v61
	v_pk_mul_f32 v[62:63], v[8:9], v[66:67] op_sel_hi:[0,1]
	v_pk_mul_f32 v[58:59], v[58:59], v[62:63]
	v_mul_f32_e32 v62, v50, v68
	v_mul_f32_e32 v63, v51, v68
	v_exp_f32_e32 v62, v62
	v_exp_f32_e32 v63, v63
	v_pk_mul_f32 v[50:51], v[50:51], v[54:55]
	v_add_f32_e32 v60, 1.0, v60
	v_add_f32_e32 v62, 1.0, v62
	v_add_f32_e32 v63, 1.0, v63
	v_rcp_f32_e32 v62, v62
	v_rcp_f32_e32 v63, v63
	v_add_f32_e32 v61, 1.0, v61
	v_rcp_f32_e32 v60, v60
	v_rcp_f32_e32 v61, v61
	v_pk_mul_f32 v[54:55], v[8:9], v[62:63] op_sel_hi:[0,1]
	v_pk_mul_f32 v[54:55], v[50:51], v[54:55]
	v_mul_f32_e32 v50, v52, v68
	v_mul_f32_e32 v51, v53, v68
	v_exp_f32_e32 v50, v50
	v_exp_f32_e32 v51, v51
	v_pk_mul_f32 v[60:61], v[8:9], v[60:61] op_sel_hi:[0,1]
	v_pk_mul_f32 v[60:61], v[64:65], v[60:61]
	v_add_f32_e32 v50, 1.0, v50
	v_add_f32_e32 v51, 1.0, v51
	v_rcp_f32_e32 v50, v50
	v_rcp_f32_e32 v51, v51
	v_cvt_pk_bf16_f32 v52, v54, v55
	v_mad_i64_i32 v[54:55], s[16:17], v143, s66, v[114:115]
	v_pk_mul_f32 v[50:51], v[8:9], v[50:51] op_sel_hi:[0,1]
	v_pk_mul_f32 v[56:57], v[56:57], v[50:51]
	v_cvt_pk_bf16_f32 v50, v58, v59
	v_cvt_pk_bf16_f32 v51, v60, v61
	v_cvt_pk_bf16_f32 v53, v56, v57
	v_lshl_add_u64 v[54:55], v[54:55], 0, v[116:117]
	v_mov_b32_e32 v8, v149
	global_store_dwordx4 v[54:55], v[50:53], off
	s_nop 1
	v_lshlrev_b64 v[50:51], s4, v[8:9]
	v_min_u32_e32 v8, 1, v50
	v_or_b32_e32 v8, v51, v8
	v_cvt_f32_u32_e32 v8, v8
	v_cvt_f32_u32_e32 v50, v148
	v_ldexp_f32 v8, v8, s5
	v_fmac_f32_e32 v8, 0x2f800000, v50
	v_fmamk_f32 v8, v8, 0x3a000000, v183
	v_rsq_f32_e32 v50, v8
	s_nop 0
	v_mul_f32_e32 v52, 0xbfb8aa3b, v50
	v_mul_f32_e32 v8, v50, v50
	v_mul_f32_e32 v50, v42, v52
	v_mul_f32_e32 v51, v43, v52
	v_exp_f32_e32 v50, v50
	v_exp_f32_e32 v51, v51
	v_pk_mul_f32 v[42:43], v[42:43], v[46:47]
	v_mul_f32_e32 v44, v44, v52
	v_add_f32_e32 v50, 1.0, v50
	v_add_f32_e32 v51, 1.0, v51
	v_rcp_f32_e32 v50, v50
	v_rcp_f32_e32 v51, v51
	v_mul_f32_e32 v45, v45, v52
	v_exp_f32_e32 v44, v44
	v_exp_f32_e32 v45, v45
	v_pk_mul_f32 v[46:47], v[8:9], v[50:51] op_sel_hi:[0,1]
	v_pk_mul_f32 v[42:43], v[42:43], v[46:47]
	v_mul_f32_e32 v46, v34, v52
	v_mul_f32_e32 v47, v35, v52
	v_exp_f32_e32 v46, v46
	v_exp_f32_e32 v47, v47
	v_pk_mul_f32 v[34:35], v[34:35], v[38:39]
	v_add_f32_e32 v44, 1.0, v44
	v_add_f32_e32 v46, 1.0, v46
	v_add_f32_e32 v47, 1.0, v47
	v_rcp_f32_e32 v46, v46
	v_rcp_f32_e32 v47, v47
	v_add_f32_e32 v45, 1.0, v45
	v_rcp_f32_e32 v44, v44
	v_rcp_f32_e32 v45, v45
	v_pk_mul_f32 v[38:39], v[8:9], v[46:47] op_sel_hi:[0,1]
	v_pk_mul_f32 v[38:39], v[34:35], v[38:39]
	v_mul_f32_e32 v34, v36, v52
	v_mul_f32_e32 v35, v37, v52
	v_exp_f32_e32 v34, v34
	v_exp_f32_e32 v35, v35
	v_pk_mul_f32 v[44:45], v[8:9], v[44:45] op_sel_hi:[0,1]
	v_pk_mul_f32 v[44:45], v[48:49], v[44:45]
	v_add_f32_e32 v34, 1.0, v34
	v_add_f32_e32 v35, 1.0, v35
	v_rcp_f32_e32 v34, v34
	v_rcp_f32_e32 v35, v35
	v_cvt_pk_bf16_f32 v36, v38, v39
	v_pk_mul_f32 v[34:35], v[8:9], v[34:35] op_sel_hi:[0,1]
	v_add_u32_e32 v8, 0x90, v142
	v_pk_mul_f32 v[40:41], v[40:41], v[34:35]
	v_mad_i64_i32 v[38:39], s[16:17], v8, s66, v[114:115]
	v_cvt_pk_bf16_f32 v34, v42, v43
	v_cvt_pk_bf16_f32 v35, v44, v45
	v_cvt_pk_bf16_f32 v37, v40, v41
	v_lshl_add_u64 v[38:39], v[38:39], 0, v[116:117]
	v_mov_b32_e32 v8, v147
	global_store_dwordx4 v[38:39], v[34:37], off
	s_nop 1
	v_lshlrev_b64 v[34:35], s4, v[8:9]
	v_min_u32_e32 v8, 1, v34
	v_or_b32_e32 v8, v35, v8
	v_cvt_f32_u32_e32 v8, v8
	v_cvt_f32_u32_e32 v34, v146
	v_ldexp_f32 v8, v8, s5
	v_fmac_f32_e32 v8, 0x2f800000, v34
	v_fmamk_f32 v8, v8, 0x3a000000, v183
	v_rsq_f32_e32 v34, v8
	s_nop 0
	v_mul_f32_e32 v36, 0xbfb8aa3b, v34
	v_mul_f32_e32 v8, v34, v34
	v_mul_f32_e32 v34, v26, v36
	v_mul_f32_e32 v35, v27, v36
	v_exp_f32_e32 v34, v34
	v_exp_f32_e32 v35, v35
	v_pk_mul_f32 v[26:27], v[26:27], v[30:31]
	v_mul_f32_e32 v28, v28, v36
	v_add_f32_e32 v34, 1.0, v34
	v_add_f32_e32 v35, 1.0, v35
	v_rcp_f32_e32 v34, v34
	v_rcp_f32_e32 v35, v35
	v_mul_f32_e32 v29, v29, v36
	v_exp_f32_e32 v28, v28
	v_exp_f32_e32 v29, v29
	v_pk_mul_f32 v[30:31], v[8:9], v[34:35] op_sel_hi:[0,1]
	v_pk_mul_f32 v[26:27], v[26:27], v[30:31]
	v_mul_f32_e32 v30, v18, v36
	v_mul_f32_e32 v31, v19, v36
	v_exp_f32_e32 v30, v30
	v_exp_f32_e32 v31, v31
	v_pk_mul_f32 v[18:19], v[18:19], v[22:23]
	v_add_f32_e32 v28, 1.0, v28
	v_add_f32_e32 v30, 1.0, v30
	v_add_f32_e32 v31, 1.0, v31
	v_rcp_f32_e32 v30, v30
	v_rcp_f32_e32 v31, v31
	v_add_f32_e32 v29, 1.0, v29
	v_rcp_f32_e32 v28, v28
	v_rcp_f32_e32 v29, v29
	v_pk_mul_f32 v[22:23], v[8:9], v[30:31] op_sel_hi:[0,1]
	v_pk_mul_f32 v[22:23], v[18:19], v[22:23]
	v_mul_f32_e32 v18, v20, v36
	v_mul_f32_e32 v19, v21, v36
	v_exp_f32_e32 v18, v18
	v_exp_f32_e32 v19, v19
	v_pk_mul_f32 v[28:29], v[8:9], v[28:29] op_sel_hi:[0,1]
	v_pk_mul_f32 v[28:29], v[32:33], v[28:29]
	v_add_f32_e32 v18, 1.0, v18
	v_add_f32_e32 v19, 1.0, v19
	v_rcp_f32_e32 v18, v18
	v_rcp_f32_e32 v19, v19
	v_cvt_pk_bf16_f32 v20, v22, v23
	v_pk_mul_f32 v[18:19], v[8:9], v[18:19] op_sel_hi:[0,1]
	v_add_u32_e32 v8, 0xa0, v142
	v_pk_mul_f32 v[24:25], v[24:25], v[18:19]
	v_mad_i64_i32 v[22:23], s[16:17], v8, s66, v[114:115]
	v_cvt_pk_bf16_f32 v18, v26, v27
	v_cvt_pk_bf16_f32 v19, v28, v29
	v_cvt_pk_bf16_f32 v21, v24, v25
	v_lshl_add_u64 v[22:23], v[22:23], 0, v[116:117]
	v_mov_b32_e32 v8, v145
	global_store_dwordx4 v[22:23], v[18:21], off
	s_nop 1
	v_lshlrev_b64 v[18:19], s4, v[8:9]
	v_min_u32_e32 v8, 1, v18
	v_or_b32_e32 v8, v19, v8
	v_cvt_f32_u32_e32 v8, v8
	v_cvt_f32_u32_e32 v18, v144
	v_ldexp_f32 v8, v8, s5
	v_fmac_f32_e32 v8, 0x2f800000, v18
	v_fmamk_f32 v8, v8, 0x3a000000, v183
	v_rsq_f32_e32 v18, v8
	s_nop 0
	v_mul_f32_e32 v20, 0xbfb8aa3b, v18
	v_mul_f32_e32 v8, v18, v18
	v_mul_f32_e32 v18, v10, v20
	v_mul_f32_e32 v19, v11, v20
	v_exp_f32_e32 v18, v18
	v_exp_f32_e32 v19, v19
	v_pk_mul_f32 v[10:11], v[10:11], v[14:15]
	v_mul_f32_e32 v12, v12, v20
	v_add_f32_e32 v18, 1.0, v18
	v_add_f32_e32 v19, 1.0, v19
	v_rcp_f32_e32 v18, v18
	v_rcp_f32_e32 v19, v19
	v_mul_f32_e32 v13, v13, v20
	v_exp_f32_e32 v12, v12
	v_exp_f32_e32 v13, v13
	v_pk_mul_f32 v[14:15], v[8:9], v[18:19] op_sel_hi:[0,1]
	v_pk_mul_f32 v[10:11], v[10:11], v[14:15]
	v_mul_f32_e32 v14, v4, v20
	v_mul_f32_e32 v15, v5, v20
	v_exp_f32_e32 v14, v14
	v_exp_f32_e32 v15, v15
	v_add_f32_e32 v12, 1.0, v12
	v_add_f32_e32 v13, 1.0, v13
	v_add_f32_e32 v14, 1.0, v14
	v_add_f32_e32 v15, 1.0, v15
	v_rcp_f32_e32 v14, v14
	v_rcp_f32_e32 v15, v15
	v_rcp_f32_e32 v12, v12
	v_rcp_f32_e32 v13, v13
	v_pk_mul_f32 v[4:5], v[8:9], v[14:15] op_sel_hi:[0,1]
	v_pk_mul_f32 v[4:5], v[0:1], v[4:5]
	v_mul_f32_e32 v0, v6, v20
	v_mul_f32_e32 v1, v7, v20
	v_exp_f32_e32 v0, v0
	v_exp_f32_e32 v1, v1
	v_pk_mul_f32 v[12:13], v[8:9], v[12:13] op_sel_hi:[0,1]
	v_pk_mul_f32 v[12:13], v[16:17], v[12:13]
	v_add_f32_e32 v0, 1.0, v0
	v_add_f32_e32 v1, 1.0, v1
	v_rcp_f32_e32 v0, v0
	v_rcp_f32_e32 v1, v1
	s_nop 0
	v_pk_mul_f32 v[0:1], v[8:9], v[0:1] op_sel_hi:[0,1]
	v_add_u32_e32 v8, 0xb0, v142
	v_pk_mul_f32 v[6:7], v[2:3], v[0:1]
	v_cvt_pk_bf16_f32 v2, v4, v5
	v_mad_i64_i32 v[4:5], s[4:5], v8, s66, v[114:115]
	v_cvt_pk_bf16_f32 v0, v10, v11
	v_cvt_pk_bf16_f32 v1, v12, v13
	v_cvt_pk_bf16_f32 v3, v6, v7
	v_lshl_add_u64 v[4:5], v[4:5], 0, v[116:117]
	global_store_dwordx4 v[4:5], v[0:3], off
	s_mov_b64 s[4:5], -1
	s_cbranch_vccnz .LBB0_939
	s_andn2_b64 vcc, exec, s[18:19]
	s_cbranch_vccnz .LBB0_938
	s_barrier
	s_branch .LBB0_938
